# v61 + P3 critical-path rebalancing: the sc>=12 workgroups (longest passC carry-in) hand their skinny-GEMM unit to their sc-12 siblings (shortest carry-in); 256-workgroup grid only
# speedup vs baseline: 1.0063x; 1.0063x over previous
; __global__ void __launch_bounds__(NTHR, 2) mk_fwd(Args args) {
;     ...
;         hgrn_passC(lds, QG, OL, DS, DSC, ZG, a_gnorm, OG, out + O_SP, bid, G, tid);
;         skinny_gemm<0, 1, 2, D>(lds, OGS, DS_, WA_OUT, D / 32, Y1S, x_s, D, nullptr, bid, G, tid, 0, SkNorm{nullptr, norm_ffn, HS, SSQS});
.LBB0_463:
	s_cmpk_gt_u32 s2, 0xff
	v_readfirstlane_b32 s3, v27
	s_cbranch_scc1 .LBB0_475
	s_cmpk_eq_u32 s28, 0x100
	s_cselect_b32 s100, 1, 0
	s_and_b32 s101, s2, 12
	s_cmp_eq_u32 s101, 12
	s_cselect_b32 s101, s100, 0
	s_cmp_lg_u32 s101, 0
	s_cbranch_scc1 .LBB0_475
	s_waitcnt lgkmcnt(0)
	s_add_u32 s8, s10, 0x4ee00000
	s_addc_u32 s9, s11, 0
	s_load_dwordx2 s[14:15], s[12:13], 0x8
	s_load_dwordx2 s[16:17], s[12:13], 0x40
	s_add_u32 s12, s10, 0x4e800000
	s_addc_u32 s13, s11, 0
	s_add_u32 s18, s10, 0x138000
	s_addc_u32 s19, s11, 0
	s_and_b32 s4, s3, 0xffffffc0
	s_ashr_i32 s5, s4, 31
	s_lshl_b64 s[4:5], s[4:5], 1
	s_add_u32 s6, s10, s4
	s_addc_u32 s7, s11, s5
	v_lshlrev_b32_e32 v8, 5, v67
	v_mov_b32_e32 v9, 0
	v_lshl_add_u64 v[0:1], s[6:7], 0, v[8:9]
	s_mov_b64 s[6:7], 0x4ed00000
	v_lshl_add_u64 v[10:11], v[0:1], 0, s[6:7]
	v_lshlrev_b32_e32 v0, 12, v31
	v_mov_b32_e32 v1, v9
	v_lshl_add_u64 v[0:1], s[10:11], 0, v[0:1]
	v_lshl_add_u64 v[0:1], v[0:1], 0, s[4:5]
	s_lshr_b32 s3, s3, 1
	v_lshl_add_u64 v[0:1], v[0:1], 0, v[8:9]
	s_mov_b64 s[4:5], 0x2200000
	s_and_b32 s3, s3, 0xfffffe0
	v_lshl_add_u64 v[12:13], v[0:1], 0, s[4:5]
	v_lshl_or_b32 v0, v67, 2, s3
	s_movk_i32 s3, 0x80
	v_cmp_gt_i32_e64 s[4:5], s3, v27
	s_movk_i32 s3, 0x90
	s_waitcnt lgkmcnt(0)
	s_cmp_lg_u64 s[14:15], 0
	v_mul_lo_u32 v0, v0, s3
	s_cselect_b64 s[10:11], -1, 0
	s_cmp_lg_u64 s[16:17], 0
	v_and_b32_e32 v1, 3, v66
	v_add3_u32 v15, 0, v0, v16
	v_mbcnt_lo_u32_b32 v0, -1, 0
	s_cselect_b64 s[22:23], -1, 0
	s_mov_b32 s39, 0
	v_lshl_add_u32 v14, v1, 5, 0
	v_lshlrev_b32_e32 v17, 3, v1
	v_cmp_eq_u32_e64 s[6:7], 0, v1
	s_mov_b32 s21, 0x12000
	s_movk_i32 s29, 0x1180
	s_movk_i32 s30, 0xfe7f
	v_add_u32_e32 v26, 0x800, v15
	v_mbcnt_hi_u32_b32 v28, -1, v0
	s_mov_b32 s31, s2
	s_branch .LBB0_466
.LBB0_465:
	s_or_b64 exec, exec, s[40:41]
	s_and_b32 s101, s2, 12
	s_cmp_eq_u32 s101, 0
	s_cselect_b32 s101, 12, 0x100
	s_add_i32 s101, s2, s101
	s_cmp_eq_u32 s31, s2
	s_cselect_b32 s101, s101, 0x100
	s_add_i32 s31, s31, s28
	s_cmp_lg_u32 s100, 0
	s_cselect_b32 s31, s101, s31
	s_cmpk_gt_u32 s31, 0xff
	s_waitcnt lgkmcnt(0)
	s_barrier
	s_cbranch_scc1 .LBB0_475
